# P5 layer-1 weight-copy loop: counted waits vmcnt(63) per item instead of one vmcnt(0) per three items (two items' loads stay in flight)
# speedup vs baseline: 1.0015x; 1.0015x over previous
; __device__ __forceinline__ void tr_load_nc(const float* W, int N, int mat, int item, int lane, int nblk, float (&x)[32]) {
;     const int kb = item / nblk, nb = item % nblk, k0 = 64 * kb, n0 = 32 * nb;
;     const int sc = src_col(mat, n0 + (lane & 31));
;     const float* wp = W + (size_t)(k0 + (lane >> 5)) * N + sc;
; #pragma unroll
;     for (int i = 0; i < 32; ++i) x[i] = wp[(size_t)(2 * i) * N];
; }
; __global__ void __launch_bounds__(NTHREADS, 2) fwd(Args a) {
;     ...
;             auto ldi = [&](int jj, float (&xx)[32]) { tr_load_nc(a.in[I_GWIN], 3 * CW, 2, jj < L1_P5 ? jj : L1_P5 - 1, lane, TR_NB2, xx); };
;             auto sti = [&](int jj, const float (&xx)[32]) { tr_store((bf16*)(a.ws + WS_WGIN), D, scr, jj, lane, TR_NB2, xx); };
;             float xc[32];
;             ldi(j, x); ldi(j + jst, xn);
;             while (j + 2 * jst < L1_P5) {
;                 ldi(j + 2 * jst, xc); sti(j, x);
;                 ldi(j + 3 * jst, x);  sti(j + jst, xn);
;                 ldi(j + 4 * jst, xn); sti(j + 2 * jst, xc);
.LBB0_682:
	s_or_b64 exec, exec, s[4:5]
	v_readlane_b32 s76, v254, 2
	v_readlane_b32 s84, v254, 10
	v_readlane_b32 s85, v254, 11
	v_lshl_or_b32 v5, s1, 6, v7
	s_ashr_i32 s1, s0, 31
	v_mov_b64_e32 v[24:25], s[84:85]
	v_mad_i64_i32 v[24:25], s[4:5], v5, s11, v[24:25]
	v_ashrrev_i32_e32 v5, 31, v4
	v_lshl_add_u64 v[4:5], v[4:5], 2, v[24:25]
	v_add_co_u32_e32 v26, vcc, 0x48000, v4
	v_add_u32_e32 v78, s14, v78
	s_nop 0
	v_addc_co_u32_e32 v27, vcc, 0, v5, vcc
	v_add_co_u32_e32 v28, vcc, 0x90000, v4
	v_readlane_b32 s77, v254, 3
	s_nop 0
	v_addc_co_u32_e32 v29, vcc, 0, v5, vcc
	v_add_co_u32_e32 v30, vcc, 0xd8000, v4
	v_readlane_b32 s78, v254, 4
	s_nop 0
	v_addc_co_u32_e32 v31, vcc, 0, v5, vcc
	v_add_co_u32_e32 v40, vcc, 0x120000, v4
	v_readlane_b32 s79, v254, 5
	s_nop 0
	v_addc_co_u32_e32 v41, vcc, 0, v5, vcc
	v_add_co_u32_e32 v42, vcc, 0x168000, v4
	v_readlane_b32 s80, v254, 6
	s_nop 0
	v_addc_co_u32_e32 v43, vcc, 0, v5, vcc
	v_add_co_u32_e32 v44, vcc, 0x1b0000, v4
	v_readlane_b32 s81, v254, 7
	s_nop 0
	v_addc_co_u32_e32 v45, vcc, 0, v5, vcc
	v_add_co_u32_e32 v46, vcc, 0x1f8000, v4
	v_readlane_b32 s82, v254, 8
	s_nop 0
	v_addc_co_u32_e32 v47, vcc, 0, v5, vcc
	global_load_dword v24, v[4:5], off
	s_nop 0
	global_load_dword v26, v[26:27], off
	s_nop 0
	global_load_dword v25, v[28:29], off
	s_nop 0
	global_load_dword v28, v[30:31], off
	global_load_dword v27, v[40:41], off
	s_nop 0
	global_load_dword v30, v[42:43], off
	global_load_dword v29, v[44:45], off
	global_load_dword v31, v[46:47], off
	v_add_co_u32_e32 v40, vcc, 0x240000, v4
	v_readlane_b32 s83, v254, 9
	s_nop 0
	v_addc_co_u32_e32 v41, vcc, 0, v5, vcc
	v_add_co_u32_e32 v42, vcc, 0x288000, v4
	v_readlane_b32 s86, v254, 12
	s_nop 0
	v_addc_co_u32_e32 v43, vcc, 0, v5, vcc
	v_add_co_u32_e32 v44, vcc, 0x2d0000, v4
	v_readlane_b32 s87, v254, 13
	s_nop 0
	v_addc_co_u32_e32 v45, vcc, 0, v5, vcc
	v_add_co_u32_e32 v46, vcc, 0x318000, v4
	v_readlane_b32 s88, v254, 14
	s_nop 0
	v_addc_co_u32_e32 v47, vcc, 0, v5, vcc
	v_add_co_u32_e32 v56, vcc, 0x360000, v4
	v_readlane_b32 s89, v254, 15
	s_nop 0
	v_addc_co_u32_e32 v57, vcc, 0, v5, vcc
	v_add_co_u32_e32 v58, vcc, 0x3a8000, v4
	v_readlane_b32 s90, v254, 16
	s_nop 0
	v_addc_co_u32_e32 v59, vcc, 0, v5, vcc
	v_add_co_u32_e32 v60, vcc, 0x3f0000, v4
	v_readlane_b32 s91, v254, 17
	s_nop 0
	v_addc_co_u32_e32 v61, vcc, 0, v5, vcc
	v_add_co_u32_e32 v62, vcc, 0x438000, v4
	s_nop 1
	v_addc_co_u32_e32 v63, vcc, 0, v5, vcc
	global_load_dword v40, v[40:41], off
	s_nop 0
	global_load_dword v42, v[42:43], off
	s_nop 0
	global_load_dword v41, v[44:45], off
	s_nop 0
	global_load_dword v44, v[46:47], off
	global_load_dword v43, v[56:57], off
	s_nop 0
	global_load_dword v46, v[58:59], off
	global_load_dword v45, v[60:61], off
	global_load_dword v47, v[62:63], off
	v_add_co_u32_e32 v56, vcc, 0x480000, v4
	s_nop 1
	v_addc_co_u32_e32 v57, vcc, 0, v5, vcc
	v_add_co_u32_e32 v58, vcc, 0x4c8000, v4
	s_nop 1
	v_addc_co_u32_e32 v59, vcc, 0, v5, vcc
	v_add_co_u32_e32 v60, vcc, 0x510000, v4
	s_nop 1
	v_addc_co_u32_e32 v61, vcc, 0, v5, vcc
	v_add_co_u32_e32 v62, vcc, 0x558000, v4
	s_nop 1
	v_addc_co_u32_e32 v63, vcc, 0, v5, vcc
	v_add_co_u32_e32 v66, vcc, 0x5a0000, v4
	s_nop 1
	v_addc_co_u32_e32 v67, vcc, 0, v5, vcc
	v_add_co_u32_e32 v70, vcc, 0x5e8000, v4
	s_nop 1
	v_addc_co_u32_e32 v71, vcc, 0, v5, vcc
	v_add_co_u32_e32 v72, vcc, 0x630000, v4
	s_nop 1
	v_addc_co_u32_e32 v73, vcc, 0, v5, vcc
	v_add_co_u32_e32 v118, vcc, 0x678000, v4
	s_nop 1
	v_addc_co_u32_e32 v119, vcc, 0, v5, vcc
	global_load_dword v56, v[56:57], off
	s_nop 0
	global_load_dword v58, v[58:59], off
	s_nop 0
	global_load_dword v57, v[60:61], off
	s_nop 0
	global_load_dword v60, v[62:63], off
	global_load_dword v59, v[66:67], off
	s_nop 0
	global_load_dword v62, v[70:71], off
	global_load_dword v61, v[72:73], off
	global_load_dword v63, v[118:119], off
	v_add_co_u32_e32 v66, vcc, 0x6c0000, v4
	s_nop 1
	v_addc_co_u32_e32 v67, vcc, 0, v5, vcc
	v_add_co_u32_e32 v70, vcc, 0x708000, v4
	s_nop 1
	v_addc_co_u32_e32 v71, vcc, 0, v5, vcc
	v_add_co_u32_e32 v72, vcc, 0x750000, v4
	s_nop 1
	v_addc_co_u32_e32 v73, vcc, 0, v5, vcc
	v_add_co_u32_e32 v118, vcc, 0x798000, v4
	s_nop 1
	v_addc_co_u32_e32 v119, vcc, 0, v5, vcc
	v_add_co_u32_e32 v120, vcc, 0x7e0000, v4
	s_nop 1
	v_addc_co_u32_e32 v121, vcc, 0, v5, vcc
	v_add_co_u32_e32 v122, vcc, 0x828000, v4
	s_nop 1
	v_addc_co_u32_e32 v123, vcc, 0, v5, vcc
	v_add_co_u32_e32 v124, vcc, 0x870000, v4
	s_nop 1
	v_addc_co_u32_e32 v125, vcc, 0, v5, vcc
	v_add_co_u32_e32 v4, vcc, 0x8b8000, v4
	s_nop 1
	v_addc_co_u32_e32 v5, vcc, 0, v5, vcc
	global_load_dword v64, v[66:67], off
	s_nop 0
	global_load_dword v67, v[70:71], off
	global_load_dword v66, v[72:73], off
	s_nop 0
	global_load_dword v70, v[118:119], off
	global_load_dword v69, v[120:121], off
	global_load_dword v72, v[122:123], off
	global_load_dword v71, v[124:125], off
	global_load_dword v73, v[4:5], off
	s_waitcnt vmcnt(63)
; #define GAS __attribute__((address_space(1)))
; #define LAS __attribute__((address_space(3)))
; #define LDS_WAIT() asm volatile("s_waitcnt lgkmcnt(0)" ::: "memory")
; __device__ __forceinline__ unsigned pk2(float lo, float hi) { return pg8::cvt_pk_bf16(lo, hi); }
; __device__ __forceinline__ void tr_store(bf16* WT, int K, LAS float* scr, int item, int lane, int nblk, const float (&x)[32]) {
;     const int kb = item / nblk, nb = item % nblk, k0 = 64 * kb, n0 = 32 * nb;
; #pragma unroll
;     for (int i = 0; i < 32; ++i) { const int kk = 2 * i + (lane >> 5); scr[kk * 33 + (lane & 31)] = x[i]; }
;     LDS_WAIT(); asm volatile("" ::: "memory");
;     const int c = lane & 7;
; #pragma unroll
;     for (int j = 0; j < 4; ++j) { const int n = (lane >> 3) + 8 * j; const LAS float* s = scr + (8 * c) * 33 + n;
;         v4u o; o.x = pk2(s[0 * 33], s[1 * 33]); o.y = pk2(s[2 * 33], s[3 * 33]); o.z = pk2(s[4 * 33], s[5 * 33]); o.w = pk2(s[6 * 33], s[7 * 33]);
;         *(GAS v4u*)(WT + (size_t)(n0 + n) * K + k0 + 8 * c) = o; }
;     LDS_WAIT(); asm volatile("" ::: "memory");
; }
	ds_write2_b32 v65, v79, v80 offset1:66
	ds_write2_b32 v65, v81, v82 offset0:132 offset1:198
	ds_write2_b32 v111, v83, v84 offset0:8 offset1:74
	ds_write2_b32 v111, v85, v86 offset0:140 offset1:206
	ds_write2_b32 v112, v87, v88 offset0:16 offset1:82
	ds_write2_b32 v112, v89, v90 offset0:148 offset1:214
	ds_write2_b32 v113, v91, v92 offset0:24 offset1:90
	ds_write2_b32 v113, v93, v94 offset0:156 offset1:222
	ds_write2_b32 v114, v95, v96 offset0:32 offset1:98
	ds_write2_b32 v114, v97, v98 offset0:164 offset1:230
	ds_write2_b32 v115, v99, v100 offset0:40 offset1:106
	ds_write2_b32 v115, v101, v102 offset0:172 offset1:238
	ds_write2_b32 v116, v103, v104 offset0:48 offset1:114
	ds_write2_b32 v116, v105, v106 offset0:180 offset1:246
	ds_write2_b32 v117, v107, v108 offset0:56 offset1:122
	ds_write2_b32 v117, v109, v110 offset0:188 offset1:254
	s_waitcnt lgkmcnt(0)
	ds_read2_b32 v[4:5], v74 offset1:33
	s_waitcnt lgkmcnt(0)
	v_cvt_pk_bf16_f32 v80, v4, v5
	ds_read2_b32 v[4:5], v74 offset0:66 offset1:99
	s_waitcnt lgkmcnt(0)
	v_cvt_pk_bf16_f32 v81, v4, v5
	ds_read2_b32 v[4:5], v74 offset0:132 offset1:165
	s_waitcnt lgkmcnt(0)
	v_cvt_pk_bf16_f32 v82, v4, v5
	ds_read2_b32 v[4:5], v74 offset0:198 offset1:231
	s_waitcnt lgkmcnt(0)
	v_cvt_pk_bf16_f32 v83, v4, v5
	v_or_b32_e32 v4, s19, v68
	v_ashrrev_i32_e32 v5, 31, v4
	v_lshl_add_u64 v[84:85], s[0:1], 1, v[2:3]
	v_lshlrev_b64 v[4:5], 13, v[4:5]
	v_lshl_add_u64 v[4:5], v[84:85], 0, v[4:5]
	ds_read2_b32 v[86:87], v74 offset0:8 offset1:41
	global_store_dwordx4 v[4:5], v[80:83], off
	s_add_i32 s0, s10, s12
	s_cmpk_lt_i32 s0, 0x7000
	s_waitcnt lgkmcnt(0)
	v_cvt_pk_bf16_f32 v80, v86, v87
	ds_read2_b32 v[4:5], v74 offset0:74 offset1:107
	s_waitcnt lgkmcnt(0)
	v_cvt_pk_bf16_f32 v81, v4, v5
	ds_read2_b32 v[4:5], v74 offset0:140 offset1:173
	s_waitcnt lgkmcnt(0)
	v_cvt_pk_bf16_f32 v82, v4, v5
	ds_read2_b32 v[4:5], v74 offset0:206 offset1:239
	s_waitcnt lgkmcnt(0)
	v_cvt_pk_bf16_f32 v83, v4, v5
	v_or_b32_e32 v4, s19, v75
	v_ashrrev_i32_e32 v5, 31, v4
	v_lshlrev_b64 v[4:5], 13, v[4:5]
	v_lshl_add_u64 v[4:5], v[84:85], 0, v[4:5]
	ds_read2_b32 v[86:87], v74 offset0:16 offset1:49
	global_store_dwordx4 v[4:5], v[80:83], off
	s_waitcnt lgkmcnt(0)
	s_nop 0
	v_cvt_pk_bf16_f32 v80, v86, v87
	ds_read2_b32 v[4:5], v74 offset0:82 offset1:115
	s_waitcnt lgkmcnt(0)
	v_cvt_pk_bf16_f32 v81, v4, v5
	ds_read2_b32 v[4:5], v74 offset0:148 offset1:181
	s_waitcnt lgkmcnt(0)
	v_cvt_pk_bf16_f32 v82, v4, v5
	ds_read2_b32 v[4:5], v74 offset0:214 offset1:247
	s_waitcnt lgkmcnt(0)
	v_cvt_pk_bf16_f32 v83, v4, v5
	v_or_b32_e32 v4, s19, v76
	v_ashrrev_i32_e32 v5, 31, v4
	v_lshlrev_b64 v[4:5], 13, v[4:5]
	v_lshl_add_u64 v[4:5], v[84:85], 0, v[4:5]
	ds_read2_b32 v[86:87], v74 offset0:24 offset1:57
	global_store_dwordx4 v[4:5], v[80:83], off
	s_waitcnt lgkmcnt(0)
	s_nop 0
	v_cvt_pk_bf16_f32 v80, v86, v87
	ds_read2_b32 v[4:5], v74 offset0:90 offset1:123
	s_waitcnt lgkmcnt(0)
	v_cvt_pk_bf16_f32 v81, v4, v5
	ds_read2_b32 v[4:5], v74 offset0:156 offset1:189
	s_waitcnt lgkmcnt(0)
	v_cvt_pk_bf16_f32 v82, v4, v5
	ds_read2_b32 v[4:5], v74 offset0:222 offset1:255
	s_waitcnt lgkmcnt(0)
	v_cvt_pk_bf16_f32 v83, v4, v5
	v_or_b32_e32 v4, s19, v77
	v_ashrrev_i32_e32 v5, 31, v4
	v_lshlrev_b64 v[4:5], 13, v[4:5]
	v_lshl_add_u64 v[4:5], v[84:85], 0, v[4:5]
	global_store_dwordx4 v[4:5], v[80:83], off
	s_waitcnt lgkmcnt(0)
	s_cbranch_scc0 .LBB0_707

; __device__ __forceinline__ int src_col(int mat, int c) {
;     ...
;     if (mat == 2) {
;         if (c < CW) return CW + c;
;         const int cc = c - CW, tile = cc >> 8, w = cc & 255;
;         return w < 128 ? (tile * 128 + w) : (2 * CW + tile * 128 + (w - 128));
;     }
;     return c;
; }
; __device__ __forceinline__ void tr_load(const float* W, int N, int mat, int item, int lane, int nblk, float (&x)[32]) {
;     const int kb = item / nblk, nb = item % nblk, k0 = 64 * kb, n0 = 32 * nb;
;     const int sc = src_col(mat, n0 + (lane & 31));
; #pragma unroll
;     for (int i = 0; i < 32; ++i) { const int kk = 2 * i + (lane >> 5); x[i] = sc >= 0 ? W[(size_t)(k0 + kk) * N + sc] : 0.f; }
; }
; __device__ __forceinline__ void tr_load_nc(const float* W, int N, int mat, int item, int lane, int nblk, float (&x)[32]) {
;     const int kb = item / nblk, nb = item % nblk, k0 = 64 * kb, n0 = 32 * nb;
;     const int sc = src_col(mat, n0 + (lane & 31));
;     const float* wp = W + (size_t)(k0 + (lane >> 5)) * N + sc;
; #pragma unroll
;     for (int i = 0; i < 32; ++i) x[i] = wp[(size_t)(2 * i) * N];
; }
; __global__ void __launch_bounds__(NTHREADS, 2) fwd(Args a) {
;     ...
;             auto ldi = [&](int jj, float (&xx)[32]) { tr_load_nc(a.in[I_GWIN], 3 * CW, 2, jj < L1_P5 ? jj : L1_P5 - 1, lane, TR_NB2, xx); };
;             auto sti = [&](int jj, const float (&xx)[32]) { tr_store((bf16*)(a.ws + WS_WGIN), D, scr, jj, lane, TR_NB2, xx); };
;             float xc[32];
;             ldi(j, x); ldi(j + jst, xn);
;             while (j + 2 * jst < L1_P5) {
;                 ldi(j + 2 * jst, xc); sti(j, x);
;                 ldi(j + 3 * jst, x);  sti(j + jst, xn);
;                 ldi(j + 4 * jst, xn); sti(j + 2 * jst, xc);
.LBB0_689:
	s_andn2_saveexec_b64 s[0:1], s[0:1]
	v_add_u32_e32 v4, 0x3000, v5
	s_or_b64 exec, exec, s[0:1]
	v_readlane_b32 s76, v254, 2
	s_lshl_b32 s0, s6, 6
	v_readlane_b32 s84, v254, 10
	v_readlane_b32 s85, v254, 11
	v_or_b32_e32 v5, s0, v7
	s_mul_hi_i32 s1, s20, 0x38e38e39
	v_mov_b64_e32 v[80:81], s[84:85]
	v_mad_i64_i32 v[80:81], s[4:5], v5, s11, v[80:81]
	v_ashrrev_i32_e32 v5, 31, v4
	v_lshl_add_u64 v[4:5], v[4:5], 2, v[80:81]
	v_add_co_u32_e32 v80, vcc, 0x48000, v4
	s_lshr_b32 s4, s1, 31
	s_nop 0
	v_addc_co_u32_e32 v81, vcc, 0, v5, vcc
	v_add_co_u32_e32 v82, vcc, 0x90000, v4
	s_ashr_i32 s1, s1, 8
	s_nop 0
	v_addc_co_u32_e32 v83, vcc, 0, v5, vcc
	v_add_co_u32_e32 v84, vcc, 0xd8000, v4
	s_add_i32 s1, s1, s4
	s_nop 0
	v_addc_co_u32_e32 v85, vcc, 0, v5, vcc
	v_add_co_u32_e32 v86, vcc, 0x120000, v4
	s_lshl_b32 s4, s1, 6
	s_nop 0
	v_addc_co_u32_e32 v87, vcc, 0, v5, vcc
	v_add_co_u32_e32 v88, vcc, 0x168000, v4
	s_mul_i32 s1, s1, 0xffff7000
	s_nop 0
	v_addc_co_u32_e32 v89, vcc, 0, v5, vcc
	v_add_co_u32_e32 v90, vcc, 0x1b0000, v4
	s_ashr_i32 s5, s4, 31
	s_nop 0
	v_addc_co_u32_e32 v91, vcc, 0, v5, vcc
	v_add_co_u32_e32 v92, vcc, 0x1f8000, v4
	s_add_i32 s10, s20, s13
	s_nop 0
	v_addc_co_u32_e32 v93, vcc, 0, v5, vcc
	global_load_dword v79, v[4:5], off
	s_nop 0
	global_load_dword v80, v[80:81], off
	s_nop 0
	global_load_dword v81, v[82:83], off
	s_nop 0
	global_load_dword v82, v[84:85], off
	global_load_dword v83, v[86:87], off
	s_nop 0
	global_load_dword v84, v[88:89], off
	global_load_dword v85, v[90:91], off
	global_load_dword v86, v[92:93], off
	v_add_co_u32_e32 v88, vcc, 0x240000, v4
	v_readlane_b32 s77, v254, 3
	s_nop 0
	v_addc_co_u32_e32 v89, vcc, 0, v5, vcc
	v_add_co_u32_e32 v90, vcc, 0x288000, v4
	v_readlane_b32 s78, v254, 4
	s_nop 0
	v_addc_co_u32_e32 v91, vcc, 0, v5, vcc
	v_add_co_u32_e32 v92, vcc, 0x2d0000, v4
	v_readlane_b32 s79, v254, 5
	s_nop 0
	v_addc_co_u32_e32 v93, vcc, 0, v5, vcc
	v_add_co_u32_e32 v94, vcc, 0x318000, v4
	v_readlane_b32 s80, v254, 6
	s_nop 0
	v_addc_co_u32_e32 v95, vcc, 0, v5, vcc
	v_add_co_u32_e32 v96, vcc, 0x360000, v4
	v_readlane_b32 s81, v254, 7
	s_nop 0
	v_addc_co_u32_e32 v97, vcc, 0, v5, vcc
	v_add_co_u32_e32 v98, vcc, 0x3a8000, v4
	v_readlane_b32 s82, v254, 8
	s_nop 0
	v_addc_co_u32_e32 v99, vcc, 0, v5, vcc
	v_add_co_u32_e32 v100, vcc, 0x3f0000, v4
	v_readlane_b32 s83, v254, 9
	s_nop 0
	v_addc_co_u32_e32 v101, vcc, 0, v5, vcc
	v_add_co_u32_e32 v102, vcc, 0x438000, v4
	v_readlane_b32 s86, v254, 12
	s_nop 0
	v_addc_co_u32_e32 v103, vcc, 0, v5, vcc
	global_load_dword v87, v[88:89], off
	s_nop 0
	global_load_dword v88, v[90:91], off
	global_load_dword v89, v[92:93], off
	s_nop 0
	global_load_dword v90, v[94:95], off
	global_load_dword v91, v[96:97], off
	global_load_dword v92, v[98:99], off
	global_load_dword v93, v[100:101], off
	s_nop 0
	global_load_dword v94, v[102:103], off
	v_add_co_u32_e32 v96, vcc, 0x480000, v4
	v_readlane_b32 s87, v254, 13
	s_nop 0
	v_addc_co_u32_e32 v97, vcc, 0, v5, vcc
	v_add_co_u32_e32 v98, vcc, 0x4c8000, v4
	v_readlane_b32 s88, v254, 14
	s_nop 0
	v_addc_co_u32_e32 v99, vcc, 0, v5, vcc
	v_add_co_u32_e32 v100, vcc, 0x510000, v4
	v_readlane_b32 s89, v254, 15
	s_nop 0
	v_addc_co_u32_e32 v101, vcc, 0, v5, vcc
	v_add_co_u32_e32 v102, vcc, 0x558000, v4
	v_readlane_b32 s90, v254, 16
	s_nop 0
	v_addc_co_u32_e32 v103, vcc, 0, v5, vcc
	v_add_co_u32_e32 v104, vcc, 0x5a0000, v4
	v_readlane_b32 s91, v254, 17
	s_nop 0
	v_addc_co_u32_e32 v105, vcc, 0, v5, vcc
	v_add_co_u32_e32 v106, vcc, 0x5e8000, v4
	s_nop 1
	v_addc_co_u32_e32 v107, vcc, 0, v5, vcc
	v_add_co_u32_e32 v108, vcc, 0x630000, v4
	s_nop 1
	v_addc_co_u32_e32 v109, vcc, 0, v5, vcc
	v_add_co_u32_e32 v110, vcc, 0x678000, v4
	s_nop 1
	v_addc_co_u32_e32 v111, vcc, 0, v5, vcc
	global_load_dword v95, v[96:97], off
	s_nop 0
	global_load_dword v96, v[98:99], off
	global_load_dword v97, v[100:101], off
	s_nop 0
	global_load_dword v98, v[102:103], off
	global_load_dword v99, v[104:105], off
	global_load_dword v100, v[106:107], off
	global_load_dword v101, v[108:109], off
	s_nop 0
	global_load_dword v102, v[110:111], off
	v_add_co_u32_e32 v104, vcc, 0x6c0000, v4
	s_nop 1
	v_addc_co_u32_e32 v105, vcc, 0, v5, vcc
	v_add_co_u32_e32 v106, vcc, 0x708000, v4
	s_nop 1
	v_addc_co_u32_e32 v107, vcc, 0, v5, vcc
	v_add_co_u32_e32 v108, vcc, 0x750000, v4
	s_nop 1
	v_addc_co_u32_e32 v109, vcc, 0, v5, vcc
	v_add_co_u32_e32 v110, vcc, 0x798000, v4
	s_nop 1
	v_addc_co_u32_e32 v111, vcc, 0, v5, vcc
	v_add_co_u32_e32 v112, vcc, 0x7e0000, v4
	s_nop 1
	v_addc_co_u32_e32 v113, vcc, 0, v5, vcc
	v_add_co_u32_e32 v114, vcc, 0x828000, v4
	s_nop 1
	v_addc_co_u32_e32 v115, vcc, 0, v5, vcc
	v_add_co_u32_e32 v116, vcc, 0x870000, v4
	s_nop 1
	v_addc_co_u32_e32 v117, vcc, 0, v5, vcc
	v_add_co_u32_e32 v4, vcc, 0x8b8000, v4
	s_nop 1
	v_addc_co_u32_e32 v5, vcc, 0, v5, vcc
	global_load_dword v103, v[104:105], off
	s_nop 0
	global_load_dword v104, v[106:107], off
	global_load_dword v105, v[108:109], off
	s_nop 0
	global_load_dword v106, v[110:111], off
	global_load_dword v107, v[112:113], off
	global_load_dword v108, v[114:115], off
	global_load_dword v109, v[116:117], off
	s_nop 0
	global_load_dword v110, v[4:5], off
	v_add_u32_e32 v111, 0x400, v65
	v_add_u32_e32 v112, 0x800, v65
	v_add_u32_e32 v113, 0xc00, v65
	v_add_u32_e32 v114, 0x1000, v65
	v_add_u32_e32 v115, 0x1400, v65
	v_add_u32_e32 v116, 0x1800, v65
	v_add_u32_e32 v117, 0x1c00, v65
	s_waitcnt vmcnt(63)
; #define GAS __attribute__((address_space(1)))
; #define LAS __attribute__((address_space(3)))
; #define LDS_WAIT() asm volatile("s_waitcnt lgkmcnt(0)" ::: "memory")
; __device__ __forceinline__ unsigned pk2(float lo, float hi) { return pg8::cvt_pk_bf16(lo, hi); }
; __device__ __forceinline__ int src_col(int mat, int c) {
;     ...
;     if (mat == 2) {
;         if (c < CW) return CW + c;
;         const int cc = c - CW, tile = cc >> 8, w = cc & 255;
;         return w < 128 ? (tile * 128 + w) : (2 * CW + tile * 128 + (w - 128));
;     }
; __device__ __forceinline__ void tr_store(bf16* WT, int K, LAS float* scr, int item, int lane, int nblk, const float (&x)[32]) {
;     const int kb = item / nblk, nb = item % nblk, k0 = 64 * kb, n0 = 32 * nb;
; #pragma unroll
;     for (int i = 0; i < 32; ++i) { const int kk = 2 * i + (lane >> 5); scr[kk * 33 + (lane & 31)] = x[i]; }
;     LDS_WAIT(); asm volatile("" ::: "memory");
;     const int c = lane & 7;
; #pragma unroll
;     for (int j = 0; j < 4; ++j) { const int n = (lane >> 3) + 8 * j; const LAS float* s = scr + (8 * c) * 33 + n;
;         v4u o; o.x = pk2(s[0 * 33], s[1 * 33]); o.y = pk2(s[2 * 33], s[3 * 33]); o.z = pk2(s[4 * 33], s[5 * 33]); o.w = pk2(s[6 * 33], s[7 * 33]);
;         *(GAS v4u*)(WT + (size_t)(n0 + n) * K + k0 + 8 * c) = o; }
;     LDS_WAIT(); asm volatile("" ::: "memory");
; }
	ds_write2_b32 v65, v8, v11 offset1:66
	ds_write2_b32 v65, v10, v14 offset0:132 offset1:198
	ds_write2_b32 v111, v9, v13 offset0:8 offset1:74
	ds_write2_b32 v111, v12, v15 offset0:140 offset1:206
	ds_write2_b32 v112, v16, v19 offset0:16 offset1:82
	ds_write2_b32 v112, v18, v22 offset0:148 offset1:214
	ds_write2_b32 v113, v17, v21 offset0:24 offset1:90
	ds_write2_b32 v113, v20, v23 offset0:156 offset1:222
	ds_write2_b32 v114, v32, v35 offset0:32 offset1:98
	ds_write2_b32 v114, v34, v38 offset0:164 offset1:230
	ds_write2_b32 v115, v33, v37 offset0:40 offset1:106
	ds_write2_b32 v115, v36, v39 offset0:172 offset1:238
	ds_write2_b32 v116, v48, v51 offset0:48 offset1:114
	ds_write2_b32 v116, v50, v54 offset0:180 offset1:246
	ds_write2_b32 v117, v49, v53 offset0:56 offset1:122
	ds_write2_b32 v117, v52, v55 offset0:188 offset1:254
	s_waitcnt lgkmcnt(0)
	ds_read2_b32 v[4:5], v74 offset1:33
	s_waitcnt lgkmcnt(0)
	v_cvt_pk_bf16_f32 v8, v4, v5
	ds_read2_b32 v[4:5], v74 offset0:66 offset1:99
	s_waitcnt lgkmcnt(0)
	v_cvt_pk_bf16_f32 v9, v4, v5
	ds_read2_b32 v[4:5], v74 offset0:132 offset1:165
	s_waitcnt lgkmcnt(0)
	v_cvt_pk_bf16_f32 v10, v4, v5
	ds_read2_b32 v[4:5], v74 offset0:198 offset1:231
	s_waitcnt lgkmcnt(0)
	v_cvt_pk_bf16_f32 v11, v4, v5
	v_add_u32_e32 v4, s1, v78
	v_ashrrev_i32_e32 v5, 31, v4
	v_lshl_add_u64 v[12:13], s[4:5], 1, v[2:3]
	v_lshlrev_b64 v[16:17], 13, v[4:5]
	v_lshl_add_u64 v[16:17], v[12:13], 0, v[16:17]
	ds_read2_b32 v[14:15], v74 offset0:8 offset1:41
	global_store_dwordx4 v[16:17], v[8:11], off
	s_min_i32 s4, s10, 0x6fff
	s_mul_hi_i32 s1, s4, 0x38e38e39
	s_waitcnt lgkmcnt(0)
	v_cvt_pk_bf16_f32 v8, v14, v15
	ds_read2_b32 v[10:11], v74 offset0:74 offset1:107
	s_waitcnt lgkmcnt(0)
	v_cvt_pk_bf16_f32 v9, v10, v11
	ds_read2_b32 v[10:11], v74 offset0:140 offset1:173
	s_waitcnt lgkmcnt(0)
	v_cvt_pk_bf16_f32 v10, v10, v11
	ds_read2_b32 v[14:15], v74 offset0:206 offset1:239
	s_waitcnt lgkmcnt(0)
	v_cvt_pk_bf16_f32 v11, v14, v15
	v_add_u32_e32 v14, 8, v4
	v_ashrrev_i32_e32 v15, 31, v14
	v_lshlrev_b64 v[14:15], 13, v[14:15]
	v_lshl_add_u64 v[14:15], v[12:13], 0, v[14:15]
	ds_read2_b32 v[16:17], v74 offset0:16 offset1:49
	global_store_dwordx4 v[14:15], v[8:11], off
	s_lshr_b32 s5, s1, 31
	s_ashr_i32 s1, s1, 8
	s_waitcnt lgkmcnt(0)
	v_cvt_pk_bf16_f32 v8, v16, v17
	ds_read2_b32 v[10:11], v74 offset0:82 offset1:115
	s_waitcnt lgkmcnt(0)
	v_cvt_pk_bf16_f32 v9, v10, v11
	ds_read2_b32 v[10:11], v74 offset0:148 offset1:181
	s_waitcnt lgkmcnt(0)
	v_cvt_pk_bf16_f32 v10, v10, v11
	ds_read2_b32 v[14:15], v74 offset0:214 offset1:247
	s_waitcnt lgkmcnt(0)
	v_cvt_pk_bf16_f32 v11, v14, v15
	v_add_u32_e32 v14, 16, v4
	v_ashrrev_i32_e32 v15, 31, v14
	v_lshlrev_b64 v[14:15], 13, v[14:15]
	v_add_u32_e32 v4, 24, v4
	v_lshl_add_u64 v[14:15], v[12:13], 0, v[14:15]
	v_ashrrev_i32_e32 v5, 31, v4
	ds_read2_b32 v[16:17], v74 offset0:24 offset1:57
	global_store_dwordx4 v[14:15], v[8:11], off
	v_lshlrev_b64 v[4:5], 13, v[4:5]
	v_lshl_add_u64 v[4:5], v[12:13], 0, v[4:5]
	s_waitcnt lgkmcnt(0)
	v_cvt_pk_bf16_f32 v8, v16, v17
	ds_read2_b32 v[10:11], v74 offset0:90 offset1:123
	s_waitcnt lgkmcnt(0)
	v_cvt_pk_bf16_f32 v9, v10, v11
	ds_read2_b32 v[10:11], v74 offset0:156 offset1:189
	s_add_i32 s1, s1, s5
	s_waitcnt lgkmcnt(0)
	v_cvt_pk_bf16_f32 v10, v10, v11
	ds_read2_b32 v[14:15], v74 offset0:222 offset1:255
	s_waitcnt lgkmcnt(0)
	v_cvt_pk_bf16_f32 v11, v14, v15
	global_store_dwordx4 v[4:5], v[8:11], off
	s_mul_i32 s5, s1, 0x480
	s_waitcnt lgkmcnt(0)
	s_sub_i32 s4, s4, s5
	s_lshl_b32 s6, s4, 5
	v_or_b32_e32 v5, s6, v6
	v_cmp_lt_i32_e32 vcc, s17, v5
	s_and_saveexec_b64 s[4:5], vcc
	s_xor_b64 s[4:5], exec, s[4:5]
	s_cbranch_execz .LBB0_697
	s_add_i32 s21, s6, 0xffffd000
	s_lshr_b32 s21, s21, 1
	v_cmp_gt_u32_sdwa s[6:7], v5, s18 src0_sel:BYTE_0 src1_sel:DWORD
	s_and_b32 s21, s21, 0x7fffff80
	s_and_saveexec_b64 s[22:23], s[6:7]
	s_xor_b64 s[6:7], exec, s[22:23]
	v_add_u32_sdwa v4, v5, s21 dst_sel:DWORD dst_unused:UNUSED_PAD src0_sel:BYTE_0 src1_sel:DWORD
	v_add_u32_e32 v4, 0x5f80, v4
	s_andn2_saveexec_b64 s[6:7], s[6:7]
	v_or_b32_sdwa v4, s21, v5 dst_sel:DWORD dst_unused:UNUSED_PAD src0_sel:DWORD src1_sel:BYTE_0
	s_or_b64 exec, exec, s[6:7]
.LBB0_697:
	s_andn2_saveexec_b64 s[4:5], s[4:5]
	v_add_u32_e32 v4, 0x3000, v5
	s_or_b64 exec, exec, s[4:5]
	v_readlane_b32 s76, v254, 2
	v_readlane_b32 s84, v254, 10
	v_readlane_b32 s85, v254, 11
	v_lshl_or_b32 v5, s1, 6, v7
	s_add_i32 s1, s15, s20
	v_mov_b64_e32 v[8:9], s[84:85]
	v_mad_i64_i32 v[8:9], s[4:5], v5, s11, v[8:9]
	v_ashrrev_i32_e32 v5, 31, v4
	v_lshl_add_u64 v[4:5], v[4:5], 2, v[8:9]
	v_add_co_u32_e32 v10, vcc, 0x48000, v4
	s_mul_hi_i32 s4, s1, 0x38e38e39
	s_nop 0
	v_addc_co_u32_e32 v11, vcc, 0, v5, vcc
	v_add_co_u32_e32 v12, vcc, 0x90000, v4
	s_lshr_b32 s5, s4, 31
	s_nop 0
	v_addc_co_u32_e32 v13, vcc, 0, v5, vcc
	v_add_co_u32_e32 v14, vcc, 0xd8000, v4
	s_ashr_i32 s4, s4, 8
	s_nop 0
	v_addc_co_u32_e32 v15, vcc, 0, v5, vcc
	v_add_co_u32_e32 v16, vcc, 0x120000, v4
	s_add_i32 s5, s4, s5
	s_nop 0
	v_addc_co_u32_e32 v17, vcc, 0, v5, vcc
	v_add_co_u32_e32 v18, vcc, 0x168000, v4
	s_lshl_b32 s4, s5, 6
	s_nop 0
	v_addc_co_u32_e32 v19, vcc, 0, v5, vcc
	v_add_co_u32_e32 v20, vcc, 0x1b0000, v4
	s_mulk_i32 s5, 0x480
	s_nop 0
	v_addc_co_u32_e32 v21, vcc, 0, v5, vcc
	v_add_co_u32_e32 v22, vcc, 0x1f8000, v4
	s_sub_i32 s1, s1, s5
	s_nop 0
	v_addc_co_u32_e32 v23, vcc, 0, v5, vcc
	global_load_dword v8, v[4:5], off
	s_nop 0
	global_load_dword v11, v[10:11], off
	s_nop 0
	global_load_dword v10, v[12:13], off
	s_nop 0
	global_load_dword v14, v[14:15], off
	s_nop 0
	global_load_dword v9, v[16:17], off
	global_load_dword v13, v[18:19], off
; __device__ __forceinline__ void tr_load_nc(const float* W, int N, int mat, int item, int lane, int nblk, float (&x)[32]) {
;     const int kb = item / nblk, nb = item % nblk, k0 = 64 * kb, n0 = 32 * nb;
;     const int sc = src_col(mat, n0 + (lane & 31));
;     const float* wp = W + (size_t)(k0 + (lane >> 5)) * N + sc;
; #pragma unroll
;     for (int i = 0; i < 32; ++i) x[i] = wp[(size_t)(2 * i) * N];
; }
	global_load_dword v12, v[20:21], off
	global_load_dword v15, v[22:23], off
	v_add_co_u32_e32 v16, vcc, 0x240000, v4
	s_lshl_b32 s1, s1, 5
	s_nop 0
	v_addc_co_u32_e32 v17, vcc, 0, v5, vcc
	v_add_co_u32_e32 v18, vcc, 0x288000, v4
	s_ashr_i32 s5, s4, 31
	s_nop 0
	v_addc_co_u32_e32 v19, vcc, 0, v5, vcc
	v_add_co_u32_e32 v20, vcc, 0x2d0000, v4
	v_readlane_b32 s77, v254, 3
	s_nop 0
	v_addc_co_u32_e32 v21, vcc, 0, v5, vcc
	v_add_co_u32_e32 v22, vcc, 0x318000, v4
	v_readlane_b32 s78, v254, 4
	s_nop 0
	v_addc_co_u32_e32 v23, vcc, 0, v5, vcc
	v_add_co_u32_e32 v32, vcc, 0x360000, v4
	v_readlane_b32 s79, v254, 5
	s_nop 0
	v_addc_co_u32_e32 v33, vcc, 0, v5, vcc
	v_add_co_u32_e32 v34, vcc, 0x3a8000, v4
	v_readlane_b32 s80, v254, 6
	s_nop 0
	v_addc_co_u32_e32 v35, vcc, 0, v5, vcc
	v_add_co_u32_e32 v36, vcc, 0x3f0000, v4
	v_readlane_b32 s81, v254, 7
	s_nop 0
	v_addc_co_u32_e32 v37, vcc, 0, v5, vcc
	v_add_co_u32_e32 v38, vcc, 0x438000, v4
	v_readlane_b32 s82, v254, 8
	s_nop 0
	v_addc_co_u32_e32 v39, vcc, 0, v5, vcc
	global_load_dword v16, v[16:17], off
	s_nop 0
	global_load_dword v19, v[18:19], off
	s_nop 0
	global_load_dword v18, v[20:21], off
	s_nop 0
	global_load_dword v22, v[22:23], off
	s_nop 0
	global_load_dword v17, v[32:33], off
	global_load_dword v21, v[34:35], off
	global_load_dword v20, v[36:37], off
	global_load_dword v23, v[38:39], off
	v_add_co_u32_e32 v32, vcc, 0x480000, v4
	v_readlane_b32 s83, v254, 9
	s_nop 0
	v_addc_co_u32_e32 v33, vcc, 0, v5, vcc
	v_add_co_u32_e32 v34, vcc, 0x4c8000, v4
	v_readlane_b32 s86, v254, 12
	s_nop 0
	v_addc_co_u32_e32 v35, vcc, 0, v5, vcc
	v_add_co_u32_e32 v36, vcc, 0x510000, v4
	v_readlane_b32 s87, v254, 13
	s_nop 0
	v_addc_co_u32_e32 v37, vcc, 0, v5, vcc
	v_add_co_u32_e32 v38, vcc, 0x558000, v4
	v_readlane_b32 s88, v254, 14
	s_nop 0
	v_addc_co_u32_e32 v39, vcc, 0, v5, vcc
	v_add_co_u32_e32 v48, vcc, 0x5a0000, v4
	v_readlane_b32 s89, v254, 15
	s_nop 0
	v_addc_co_u32_e32 v49, vcc, 0, v5, vcc
	v_add_co_u32_e32 v50, vcc, 0x5e8000, v4
	v_readlane_b32 s90, v254, 16
	s_nop 0
	v_addc_co_u32_e32 v51, vcc, 0, v5, vcc
	v_add_co_u32_e32 v52, vcc, 0x630000, v4
	v_readlane_b32 s91, v254, 17
	s_nop 0
	v_addc_co_u32_e32 v53, vcc, 0, v5, vcc
	v_add_co_u32_e32 v54, vcc, 0x678000, v4
	s_nop 1
	v_addc_co_u32_e32 v55, vcc, 0, v5, vcc
	global_load_dword v32, v[32:33], off
	s_nop 0
	global_load_dword v35, v[34:35], off
	s_nop 0
	global_load_dword v34, v[36:37], off
	s_nop 0
	global_load_dword v38, v[38:39], off
	s_nop 0
	global_load_dword v33, v[48:49], off
	global_load_dword v37, v[50:51], off
	global_load_dword v36, v[52:53], off
	global_load_dword v39, v[54:55], off
	v_add_co_u32_e32 v48, vcc, 0x6c0000, v4
	s_nop 1
	v_addc_co_u32_e32 v49, vcc, 0, v5, vcc
	v_add_co_u32_e32 v50, vcc, 0x708000, v4
	s_nop 1
	v_addc_co_u32_e32 v51, vcc, 0, v5, vcc
	v_add_co_u32_e32 v52, vcc, 0x750000, v4
	s_nop 1
	v_addc_co_u32_e32 v53, vcc, 0, v5, vcc
	v_add_co_u32_e32 v54, vcc, 0x798000, v4
	s_nop 1
	v_addc_co_u32_e32 v55, vcc, 0, v5, vcc
	v_add_co_u32_e32 v118, vcc, 0x7e0000, v4
	s_nop 1
	v_addc_co_u32_e32 v119, vcc, 0, v5, vcc
	v_add_co_u32_e32 v120, vcc, 0x828000, v4
	s_nop 1
	v_addc_co_u32_e32 v121, vcc, 0, v5, vcc
	v_add_co_u32_e32 v122, vcc, 0x870000, v4
	s_nop 1
	v_addc_co_u32_e32 v123, vcc, 0, v5, vcc
	v_add_co_u32_e32 v4, vcc, 0x8b8000, v4
	s_nop 1
	v_addc_co_u32_e32 v5, vcc, 0, v5, vcc
	global_load_dword v48, v[48:49], off
	s_nop 0
	global_load_dword v51, v[50:51], off
	s_nop 0
	global_load_dword v50, v[52:53], off
	s_nop 0
	global_load_dword v54, v[54:55], off
	s_nop 0
	global_load_dword v49, v[118:119], off
	global_load_dword v53, v[120:121], off
	global_load_dword v52, v[122:123], off
	global_load_dword v55, v[4:5], off
	s_waitcnt vmcnt(63)
; #define GAS __attribute__((address_space(1)))
; #define LAS __attribute__((address_space(3)))
; #define LDS_WAIT() asm volatile("s_waitcnt lgkmcnt(0)" ::: "memory")
; __device__ __forceinline__ unsigned pk2(float lo, float hi) { return pg8::cvt_pk_bf16(lo, hi); }
; __device__ __forceinline__ int src_col(int mat, int c) {
;     ...
;     if (mat == 2) {
;         if (c < CW) return CW + c;
;         const int cc = c - CW, tile = cc >> 8, w = cc & 255;
;         return w < 128 ? (tile * 128 + w) : (2 * CW + tile * 128 + (w - 128));
;     }
; __device__ __forceinline__ void tr_store(bf16* WT, int K, LAS float* scr, int item, int lane, int nblk, const float (&x)[32]) {
;     const int kb = item / nblk, nb = item % nblk, k0 = 64 * kb, n0 = 32 * nb;
; #pragma unroll
;     for (int i = 0; i < 32; ++i) { const int kk = 2 * i + (lane >> 5); scr[kk * 33 + (lane & 31)] = x[i]; }
;     LDS_WAIT(); asm volatile("" ::: "memory");
;     const int c = lane & 7;
; #pragma unroll
;     for (int j = 0; j < 4; ++j) { const int n = (lane >> 3) + 8 * j; const LAS float* s = scr + (8 * c) * 33 + n;
;         v4u o; o.x = pk2(s[0 * 33], s[1 * 33]); o.y = pk2(s[2 * 33], s[3 * 33]); o.z = pk2(s[4 * 33], s[5 * 33]); o.w = pk2(s[6 * 33], s[7 * 33]);
;         *(GAS v4u*)(WT + (size_t)(n0 + n) * K + k0 + 8 * c) = o; }
;     LDS_WAIT(); asm volatile("" ::: "memory");
; }
	ds_write2_b32 v65, v24, v26 offset1:66
	ds_write2_b32 v65, v25, v28 offset0:132 offset1:198
	ds_write2_b32 v111, v27, v30 offset0:8 offset1:74
	ds_write2_b32 v111, v29, v31 offset0:140 offset1:206
	ds_write2_b32 v112, v40, v42 offset0:16 offset1:82
	ds_write2_b32 v112, v41, v44 offset0:148 offset1:214
	ds_write2_b32 v113, v43, v46 offset0:24 offset1:90
	ds_write2_b32 v113, v45, v47 offset0:156 offset1:222
	ds_write2_b32 v114, v56, v58 offset0:32 offset1:98
	ds_write2_b32 v114, v57, v60 offset0:164 offset1:230
	ds_write2_b32 v115, v59, v62 offset0:40 offset1:106
	ds_write2_b32 v115, v61, v63 offset0:172 offset1:238
	ds_write2_b32 v116, v64, v67 offset0:48 offset1:114
	ds_write2_b32 v116, v66, v70 offset0:180 offset1:246
	ds_write2_b32 v117, v69, v72 offset0:56 offset1:122
	ds_write2_b32 v117, v71, v73 offset0:188 offset1:254
	s_waitcnt lgkmcnt(0)
	ds_read2_b32 v[4:5], v74 offset1:33
	s_waitcnt lgkmcnt(0)
	v_cvt_pk_bf16_f32 v24, v4, v5
	ds_read2_b32 v[4:5], v74 offset0:66 offset1:99
	s_waitcnt lgkmcnt(0)
	v_cvt_pk_bf16_f32 v25, v4, v5
	ds_read2_b32 v[4:5], v74 offset0:132 offset1:165
	s_waitcnt lgkmcnt(0)
	v_cvt_pk_bf16_f32 v26, v4, v5
	ds_read2_b32 v[4:5], v74 offset0:198 offset1:231
	s_waitcnt lgkmcnt(0)
	v_cvt_pk_bf16_f32 v27, v4, v5
	v_or_b32_e32 v4, s1, v68
	v_ashrrev_i32_e32 v5, 31, v4
	v_lshl_add_u64 v[28:29], s[4:5], 1, v[2:3]
	v_lshlrev_b64 v[4:5], 13, v[4:5]
	v_lshl_add_u64 v[4:5], v[28:29], 0, v[4:5]
	ds_read2_b32 v[30:31], v74 offset0:8 offset1:41
	global_store_dwordx4 v[4:5], v[24:27], off
	s_waitcnt lgkmcnt(0)
	s_nop 0
	v_cvt_pk_bf16_f32 v24, v30, v31
	ds_read2_b32 v[4:5], v74 offset0:74 offset1:107
	s_waitcnt lgkmcnt(0)
	v_cvt_pk_bf16_f32 v25, v4, v5
	ds_read2_b32 v[4:5], v74 offset0:140 offset1:173
	s_waitcnt lgkmcnt(0)
	v_cvt_pk_bf16_f32 v26, v4, v5
	ds_read2_b32 v[4:5], v74 offset0:206 offset1:239
	s_waitcnt lgkmcnt(0)
	v_cvt_pk_bf16_f32 v27, v4, v5
	v_or_b32_e32 v4, s1, v75
	v_ashrrev_i32_e32 v5, 31, v4
	v_lshlrev_b64 v[4:5], 13, v[4:5]
	v_lshl_add_u64 v[4:5], v[28:29], 0, v[4:5]
	ds_read2_b32 v[30:31], v74 offset0:16 offset1:49
	global_store_dwordx4 v[4:5], v[24:27], off
	s_waitcnt lgkmcnt(0)
	s_nop 0
	v_cvt_pk_bf16_f32 v24, v30, v31
	ds_read2_b32 v[4:5], v74 offset0:82 offset1:115
	s_waitcnt lgkmcnt(0)
	v_cvt_pk_bf16_f32 v25, v4, v5
	ds_read2_b32 v[4:5], v74 offset0:148 offset1:181
	s_waitcnt lgkmcnt(0)
	v_cvt_pk_bf16_f32 v26, v4, v5
	ds_read2_b32 v[4:5], v74 offset0:214 offset1:247
	s_waitcnt lgkmcnt(0)
	v_cvt_pk_bf16_f32 v27, v4, v5
	v_or_b32_e32 v4, s1, v76
	v_ashrrev_i32_e32 v5, 31, v4
	v_lshlrev_b64 v[4:5], 13, v[4:5]
	v_lshl_add_u64 v[4:5], v[28:29], 0, v[4:5]
	ds_read2_b32 v[30:31], v74 offset0:24 offset1:57
	global_store_dwordx4 v[4:5], v[24:27], off
	s_waitcnt lgkmcnt(0)
	s_nop 0
	v_cvt_pk_bf16_f32 v24, v30, v31
	ds_read2_b32 v[4:5], v74 offset0:90 offset1:123
	s_waitcnt lgkmcnt(0)
	v_cvt_pk_bf16_f32 v25, v4, v5
	ds_read2_b32 v[4:5], v74 offset0:156 offset1:189
	s_waitcnt lgkmcnt(0)
	v_cvt_pk_bf16_f32 v26, v4, v5
	ds_read2_b32 v[4:5], v74 offset0:222 offset1:255
	s_waitcnt lgkmcnt(0)
	v_cvt_pk_bf16_f32 v27, v4, v5
	v_or_b32_e32 v4, s1, v77
	s_add_i32 s1, s16, s20
	s_min_i32 s4, s1, 0x6fff
	v_ashrrev_i32_e32 v5, 31, v4
	s_mul_hi_i32 s1, s4, 0x38e38e39
	v_lshlrev_b64 v[4:5], 13, v[4:5]
	s_lshr_b32 s5, s1, 31
	s_ashr_i32 s1, s1, 8
	v_lshl_add_u64 v[4:5], v[28:29], 0, v[4:5]
	s_add_i32 s1, s1, s5
	global_store_dwordx4 v[4:5], v[24:27], off
	s_mul_i32 s5, s1, 0x480
	s_waitcnt lgkmcnt(0)
	s_sub_i32 s4, s4, s5
	s_lshl_b32 s6, s4, 5
	v_or_b32_e32 v5, s6, v6
	v_cmp_lt_i32_e32 vcc, s17, v5
	s_and_saveexec_b64 s[4:5], vcc
	s_xor_b64 s[4:5], exec, s[4:5]
	s_cbranch_execz .LBB0_705
	s_add_i32 s20, s6, 0xffffd000
	s_lshr_b32 s20, s20, 1
	v_cmp_gt_u32_sdwa s[6:7], v5, s18 src0_sel:BYTE_0 src1_sel:DWORD
	s_and_b32 s20, s20, 0x7fffff80
	s_and_saveexec_b64 s[22:23], s[6:7]
	s_xor_b64 s[6:7], exec, s[22:23]
	v_add_u32_sdwa v4, v5, s20 dst_sel:DWORD dst_unused:UNUSED_PAD src0_sel:BYTE_0 src1_sel:DWORD
	v_add_u32_e32 v4, 0x5f80, v4
	s_andn2_saveexec_b64 s[6:7], s[6:7]
	v_or_b32_sdwa v4, s20, v5 dst_sel:DWORD dst_unused:UNUSED_PAD src0_sel:DWORD src1_sel:BYTE_0
	s_or_b64 exec, exec, s[6:7]
